# half-block 0 runs its prep part 1 items at raised wave priority (s_setprio 2 around the block, back to 0 afterwards)
# speedup vs baseline: 1.0015x; 1.0015x over previous
; DI int vb_id() { return (int)blockIdx.x + half_id() * (int)gridDim.x; }
; DI int vb_n() { return (int)gridDim.x * 2; }
; DI void phase_prep(const Params& p, char* smem, int part, int vb) {
;     ...
;   } else {
;     const int NITEMS = 1024 + 1024 + 128 + 128 + 256 + 512 + 32;
;     for (int it0 = vb; it0 < NITEMS; it0 += vb_n()) {
; __global__ void __launch_bounds__(512) fwd_megakernel(Params p) {
;     ...
;   phase_prep(p, hsm, 1, (vb_id() + vb_n() - 128) % vb_n());
.LBB0_529:
	v_writelane_b32 v253, s58, 32
	s_nop 1
	v_writelane_b32 v253, s59, 33
	v_writelane_b32 v253, s72, 34
	s_nop 1
	v_writelane_b32 v253, s73, 35
	v_writelane_b32 v253, s74, 36
	v_writelane_b32 v253, s75, 37
	v_writelane_b32 v253, s76, 38
	v_writelane_b32 v253, s77, 39
	v_writelane_b32 v253, s78, 40
	v_writelane_b32 v253, s79, 41
	v_writelane_b32 v253, s80, 42
	v_writelane_b32 v253, s81, 43
	v_writelane_b32 v253, s82, 44
	v_writelane_b32 v253, s83, 45
	v_writelane_b32 v253, s84, 46
	v_writelane_b32 v253, s85, 47
	v_writelane_b32 v253, s86, 48
	v_writelane_b32 v253, s87, 49
	s_or_b64 exec, exec, s[0:1]
	v_writelane_b32 v253, s60, 50
	v_writelane_b32 v253, s53, 51
	v_writelane_b32 v253, s56, 52
	v_readfirstlane_b32 s0, v211
	s_lshr_b32 s0, s0, 8
	v_writelane_b32 v253, s57, 53
	v_writelane_b32 v253, s54, 54
	s_mul_i32 s0, s0, s54
	s_add_i32 s94, s0, s52
	v_writelane_b32 v253, s55, 55
	s_cmpk_gt_i32 s94, 0x3ff
	s_waitcnt lgkmcnt(0)
	s_barrier
	v_writelane_b32 v253, s52, 56
	v_lshrrev_b32_e32 v250, 8, v211
	v_mul_u32_u24_e32 v250, 0x13f00, v250
	v_add_u32_e32 v250, 0x13ee0, v250
	v_bfe_u32 v249, v211, 6, 2
	v_lshl_add_u32 v249, v249, 2, v250
	v_mov_b32_e32 v251, 0
	ds_write_b32 v249, v251
	s_waitcnt lgkmcnt(0)
	s_barrier
	v_readfirstlane_b32 s0, v211
	s_nop 0
	s_lshr_b32 s0, s0, 8
	s_cmp_lg_u32 s0, 0
	s_cbranch_scc1 .Lp1a_exit
	v_readlane_b32 s74, v253, 36
	v_readlane_b32 s75, v253, 37
	v_readlane_b32 s76, v253, 38
	v_readlane_b32 s77, v253, 39
	v_readlane_b32 s78, v253, 40
	v_readlane_b32 s79, v253, 41
	v_readlane_b32 s80, v253, 42
	v_readlane_b32 s81, v253, 43
	v_readlane_b32 s86, v253, 48
	v_readlane_b32 s87, v253, 49
	s_nop 3
	s_setprio 2
	s_abs_i32 s1, s88
	v_cvt_f32_u32_e32 v0, s1
	v_readfirstlane_b32 s0, v211
	s_lshr_b32 s0, s0, 8
	s_mul_i32 s0, s0, s54
	v_rcp_iflag_f32_e32 v0, v0
	s_add_i32 s2, s52, s88
	s_sub_i32 s4, 0, s1
	s_add_i32 s0, s2, s0
	v_mul_f32_e32 v0, 0x4f7ffffe, v0
	v_cvt_u32_f32_e32 v0, v0
	s_addk_i32 s0, 0xff80
	s_ashr_i32 s2, s0, 31
	s_abs_i32 s0, s0
	v_readfirstlane_b32 s5, v0
	s_mul_i32 s4, s4, s5
	s_mul_hi_u32 s4, s5, s4
	s_add_i32 s5, s5, s4
	s_mul_hi_u32 s4, s0, s5
	s_mul_i32 s4, s4, s1
	s_sub_i32 s0, s0, s4
	s_sub_i32 s4, s0, s1
	s_cmp_ge_u32 s0, s1
	s_cselect_b32 s0, s4, s0
	s_sub_i32 s4, s0, s1
	s_cmp_ge_u32 s0, s1
	s_cselect_b32 s0, s4, s0
	s_xor_b32 s0, s0, s2
	s_sub_i32 s20, s0, s2
	s_mov_b32 s3, 0
	v_mov_b32_e32 v0, v210
	s_cmpk_gt_i32 s20, 0xc1f
	s_cbranch_scc1 .Lp1a_exit
	s_add_u32 s6, s86, 0x1180000
	s_addc_u32 s7, s87, 0
	s_add_u32 s21, s86, 0xd00000
	s_addc_u32 s22, s87, 0
	s_add_u32 s23, s86, 0xb00000
	s_addc_u32 s24, s87, 0
	s_add_u32 s25, s86, 0xa00000
	s_addc_u32 s26, s87, 0
	s_add_u32 s27, s86, 0x900000
	s_addc_u32 s28, s87, 0
	v_and_b32_e32 v2, 63, v0
	s_add_u32 s8, s86, 0x2200204
	v_ashrrev_i32_e32 v0, 4, v0
	s_addc_u32 s9, s87, 0
	v_lshlrev_b32_e32 v48, 4, v2
	v_mov_b32_e32 v49, 0
	v_and_b32_e32 v62, -4, v0
	v_lshl_add_u64 v[0:1], s[86:87], 0, v[48:49]
	s_mov_b64 s[4:5], 0x3200200
	s_add_u32 s10, s86, 0x2200200
	s_mov_b64 s[12:13], 0x1200200
	v_cmp_eq_u32_e64 s[0:1], 0, v213
	v_add_u32_e32 v63, 0xffffc000, v62
	v_lshl_add_u64 v[50:51], v[0:1], 0, s[4:5]
	v_cmp_eq_u32_e64 s[4:5], 0, v2
	s_addc_u32 s11, s87, 0
	v_lshl_add_u64 v[52:53], v[0:1], 0, s[12:13]
	v_lshl_add_u64 v[54:55], s[80:81], 0, v[48:49]
	v_lshl_add_u64 v[56:57], s[78:79], 0, v[48:49]
	s_movk_i32 s29, 0x104
	s_movk_i32 s30, 0x7fff
	s_movk_i32 s31, 0x1000
	s_movk_i32 s34, 0x2000
	s_movk_i32 s35, 0x3000
	v_mov_b32_e32 v64, 1
	v_mbcnt_hi_u32_b32 v65, -1, v212
	s_branch .Lp1a_354

; DI int vb_n() { return (int)gridDim.x * 2; }
; DI void phase_prep(const Params& p, char* smem, int part, int vb) {
;     ...
;   } else {
;     const int NITEMS = 1024 + 1024 + 128 + 128 + 256 + 512 + 32;
;     for (int it0 = vb; it0 < NITEMS; it0 += vb_n()) {
.Lp1a_exit:
	v_readfirstlane_b32 s0, v211
	s_nop 0
	s_lshr_b32 s0, s0, 8
	s_cmp_lg_u32 s0, 0
	s_cbranch_scc1 .Lp1a_prio
	s_setprio 0
